# v49 plus: P1 (input projection) epilogue stores 2..15 re-laid across lanes (quad-contiguous 64 B), lane constants recomputed per unit in registers that are dead by then
# speedup vs baseline: 1.0042x; 1.0042x over previous
; __device__ __forceinline__ unsigned cvt_pk_bf16(float lo, float hi) { unsigned r; asm volatile("v_cvt_pk_bf16_f32 %0, %1, %2" : "=v"(r) : "v"(lo), "v"(hi)); return r; }
; __device__ __forceinline__ float row_rstd(const float* part, int row, float eps) {
;     const f32x4* p = (const f32x4*)(part + (size_t)row * 16);
;     const f32x4 a = p[0], b = p[1], c = p[2], d = p[3];
;     const float s = ((a[0] + a[1]) + (a[2] + a[3])) + ((b[0] + b[1]) + (b[2] + b[3])) + ((c[0] + c[1]) + (c[2] + c[3])) + ((d[0] + d[1]) + (d[2] + d[3]));
;     return 1.0f / sqrtf(s * (1.0f / 1024.0f) + eps);
; }
;     __device__ __forceinline__ void operator()(const f32x4 (&acc)[2][2][4][2], const Unit& u, int wr, int wc, int fr, int fq) const {
;     ...
;                     v0 = v0 * scr; v1 = v1 * scr;
;                     if (nrmw) { float q = (v0[0] * v0[0] + v0[1] * v0[1]) + (v0[2] * v0[2] + v0[3] * v0[3]) + (v1[0] * v1[0] + v1[1] * v1[1]) + (v1[2] * v1[2] + v1[3] * v1[3]);
;                         q += __shfl_xor(q, 16); q += __shfl_xor(q, 32); mxn[bj] = fmaxf(mxn[bj], q); }
;                     u32x4 w; w.x = cvt_pk_bf16(v0[0], v0[1]); w.y = cvt_pk_bf16(v0[2], v0[3]); w.z = cvt_pk_bf16(v1[0], v1[1]); w.w = cvt_pk_bf16(v1[2], v1[3]);
;                     *(u32x4*)(rowp + bj * HALF) = w;
.LBB0_302:
	v_cvt_pk_bf16_f32 v180, v180, v181
	v_cvt_pk_bf16_f32 v181, v182, v183
	v_cvt_pk_bf16_f32 v182, v176, v177
	v_cvt_pk_bf16_f32 v183, v178, v179
	v_or_b32_e32 v176, 16, v208
	v_cndmask_b32_e64 v178, 0, 1, s[18:19]
	v_ashrrev_i32_e32 v177, 31, v176
	v_cmp_ne_u32_e64 s[16:17], 1, v178
	s_andn2_b64 vcc, exec, s[18:19]
	s_mov_b64 s[0:1], -1
	global_store_dwordx4 v[186:187], v[180:183], off offset:256
	v_and_b32_e32 v226, 15, v212
	v_lshrrev_b32_e32 v227, 2, v212
	v_sub_u32_e32 v227, v227, v226
	v_lshrrev_b32_e32 v226, 4, v212
	v_and_b32_e32 v253, 3, v212
	v_sub_u32_e32 v226, v253, v226
	v_lshlrev_b32_e32 v226, 4, v226
	v_mul_i32_i24_e32 v228, 0x1800, v227
	v_add_u32_e32 v228, v228, v226
	v_ashrrev_i32_e32 v229, 31, v228
	v_lshlrev_b32_e32 v253, 4, v253
	v_lshrrev_b32_e32 v226, 2, v212
	v_add_u32_e32 v253, v253, v226
	v_lshlrev_b32_e32 v253, 2, v253
	s_cbranch_vccnz .LBB0_308
	v_lshlrev_b64 v[178:179], 6, v[176:177]
	v_lshl_add_u64 v[182:183], s[22:23], 0, v[178:179]
	global_load_dwordx4 v[178:181], v[182:183], off offset:48
	global_load_dwordx4 v[186:189], v[182:183], off offset:32
	global_load_dwordx4 v[214:217], v[182:183], off offset:16
	global_load_dwordx4 v[222:225], v[182:183], off
	s_waitcnt vmcnt(0)
	v_add_f32_e32 v186, v186, v187
	v_mov_b32_e32 v190, v215
	v_mov_b32_e32 v182, v223
	v_mov_b32_e32 v183, v224
	v_mov_b32_e32 v223, v225
	v_mov_b32_e32 v191, v216
	v_mov_b32_e32 v215, v217
	v_pk_add_f32 v[182:183], v[182:183], v[222:223]
	v_pk_add_f32 v[190:191], v[190:191], v[214:215]
	v_pk_add_f32 v[182:183], v[182:183], v[182:183] op_sel:[0,1] op_sel_hi:[1,0]
	v_pk_add_f32 v[190:191], v[190:191], v[190:191] op_sel:[0,1] op_sel_hi:[1,0]
	v_add_f32_e32 v188, v188, v189
	v_mov_b32_e32 v183, v178
	v_mov_b32_e32 v191, v179
	v_mov_b32_e32 v187, v180
	v_mov_b32_e32 v189, v181
	v_pk_add_f32 v[178:179], v[182:183], v[190:191]
	v_pk_add_f32 v[180:181], v[186:187], v[188:189]
	s_nop 0
	v_pk_add_f32 v[178:179], v[178:179], v[180:181]
	s_nop 0
	v_add_f32_e32 v177, v178, v179
	v_fmamk_f32 v177, v177, 0x3a800000, v246
	v_cmp_gt_f32_e32 vcc, s83, v177
	v_mul_f32_e32 v178, 0x4f800000, v177
	s_nop 0
	v_cndmask_b32_e32 v177, v177, v178, vcc
	v_sqrt_f32_e32 v178, v177
	s_nop 0
	v_add_u32_e32 v179, -1, v178
	v_fma_f32 v180, -v179, v178, v177
	v_cmp_ge_f32_e64 s[0:1], 0, v180
	v_add_u32_e32 v180, 1, v178
	s_nop 0
	v_cndmask_b32_e64 v179, v178, v179, s[0:1]
	v_fma_f32 v178, -v180, v178, v177
	v_cmp_lt_f32_e64 s[0:1], 0, v178
	s_nop 1
	v_cndmask_b32_e64 v178, v179, v180, s[0:1]
	v_mul_f32_e32 v179, 0x37800000, v178
	v_cndmask_b32_e32 v178, v178, v179, vcc
	v_cmp_class_f32_e32 vcc, v177, v247
	s_nop 1
	v_cndmask_b32_e32 v177, v178, v177, vcc
	v_div_scale_f32 v178, s[0:1], v177, v177, 1.0
	v_rcp_f32_e32 v179, v178
	s_nop 0
	v_fma_f32 v180, -v178, v179, 1.0
	v_fmac_f32_e32 v179, v180, v179
	v_div_scale_f32 v180, vcc, 1.0, v177, 1.0
	v_mul_f32_e32 v181, v180, v179
	v_fma_f32 v182, -v178, v181, v180
	v_fmac_f32_e32 v181, v182, v179
	v_fma_f32 v178, -v178, v181, v180
	v_div_fmas_f32 v178, v178, v179, v181
	v_div_fixup_f32 v216, v178, v177, 1.0
	s_cbranch_execz .LBB0_309

; __device__ __forceinline__ unsigned cvt_pk_bf16(float lo, float hi) { unsigned r; asm volatile("v_cvt_pk_bf16_f32 %0, %1, %2" : "=v"(r) : "v"(lo), "v"(hi)); return r; }
;     __device__ __forceinline__ void operator()(const f32x4 (&acc)[2][2][4][2], const Unit& u, int wr, int wc, int fr, int fq) const {
;     ...
;                     if (ropew) {
;                         f32x4 p0, p1;
; #pragma unroll
;                         for (int e = 0; e < 4; ++e) { p0[e] = __shfl_xor(v0[e], 16); p1[e] = __shfl_xor(v1[e], 16); }
;                         v0 = v0 * c0 + p0 * s0; v1 = v1 * c1 + p1 * s1;
;                     }
;                     v0 = v0 * scr; v1 = v1 * scr;
;                     if (nrmw) { float q = (v0[0] * v0[0] + v0[1] * v0[1]) + (v0[2] * v0[2] + v0[3] * v0[3]) + (v1[0] * v1[0] + v1[1] * v1[1]) + (v1[2] * v1[2] + v1[3] * v1[3]);
;                         q += __shfl_xor(q, 16); q += __shfl_xor(q, 32); mxn[bj] = fmaxf(mxn[bj], q); }
;                     u32x4 w; w.x = cvt_pk_bf16(v0[0], v0[1]); w.y = cvt_pk_bf16(v0[2], v0[3]); w.z = cvt_pk_bf16(v1[0], v1[1]); w.w = cvt_pk_bf16(v1[2], v1[3]);
;                     *(u32x4*)(rowp + bj * HALF) = w;
.LBB0_316:
	v_mov_b64_e32 v[168:169], s[28:29]
	v_mad_i64_i32 v[168:169], s[0:1], v176, s86, v[168:169]
	v_lshl_add_u64 v[168:169], v[184:185], 1, v[168:169]
	s_and_b64 vcc, exec, s[12:13]
	v_cvt_pk_bf16_f32 v172, v172, v173
	v_cvt_pk_bf16_f32 v173, v174, v175
	v_cvt_pk_bf16_f32 v174, v218, v219
	v_cvt_pk_bf16_f32 v175, v170, v171
	ds_bpermute_b32 v222, v253, v172
	ds_bpermute_b32 v223, v253, v173
	ds_bpermute_b32 v224, v253, v174
	ds_bpermute_b32 v225, v253, v175
	v_lshl_add_u64 v[226:227], v[168:169], 0, v[228:229]
	s_cbranch_vccnz .LBB0_318
	ds_bpermute_b32 v170, v235, v164
	ds_bpermute_b32 v171, v235, v165
	ds_bpermute_b32 v172, v235, v160
	ds_bpermute_b32 v174, v235, v166
	ds_bpermute_b32 v175, v235, v167
	ds_bpermute_b32 v173, v235, v161
	ds_bpermute_b32 v176, v235, v162
	ds_bpermute_b32 v177, v235, v163
	s_waitcnt lgkmcnt(0)
	v_pk_mul_f32 v[170:171], v[188:189], v[170:171]
	v_pk_mul_f32 v[174:175], v[190:191], v[174:175]
	v_pk_fma_f32 v[164:165], v[164:165], v[214:215], v[170:171]
	v_pk_mul_f32 v[170:171], v[182:183], v[172:173]
	v_pk_mul_f32 v[172:173], v[180:181], v[176:177]
	v_pk_fma_f32 v[166:167], v[166:167], v[210:211], v[174:175]
	v_pk_fma_f32 v[162:163], v[162:163], v[178:179], v[172:173]
	v_pk_fma_f32 v[160:161], v[160:161], v[186:187], v[170:171]

; __device__ __forceinline__ unsigned cvt_pk_bf16(float lo, float hi) { unsigned r; asm volatile("v_cvt_pk_bf16_f32 %0, %1, %2" : "=v"(r) : "v"(lo), "v"(hi)); return r; }
; __device__ __forceinline__ float row_rstd(const float* part, int row, float eps) {
;     const f32x4* p = (const f32x4*)(part + (size_t)row * 16);
;     const f32x4 a = p[0], b = p[1], c = p[2], d = p[3];
;     const float s = ((a[0] + a[1]) + (a[2] + a[3])) + ((b[0] + b[1]) + (b[2] + b[3])) + ((c[0] + c[1]) + (c[2] + c[3])) + ((d[0] + d[1]) + (d[2] + d[3]));
;     return 1.0f / sqrtf(s * (1.0f / 1024.0f) + eps);
; }
;     __device__ __forceinline__ void operator()(const f32x4 (&acc)[2][2][4][2], const Unit& u, int wr, int wc, int fr, int fq) const {
;     ...
;                     u32x4 w; w.x = cvt_pk_bf16(v0[0], v0[1]); w.y = cvt_pk_bf16(v0[2], v0[3]); w.z = cvt_pk_bf16(v1[0], v1[1]); w.w = cvt_pk_bf16(v1[2], v1[3]);
;                     *(u32x4*)(rowp + bj * HALF) = w;
.LBB0_322:
	v_cvt_pk_bf16_f32 v164, v164, v165
	v_cvt_pk_bf16_f32 v165, v166, v167
	v_cvt_pk_bf16_f32 v166, v160, v161
	v_or_b32_e32 v160, 32, v208
	v_ashrrev_i32_e32 v161, 31, v160
	s_and_b64 vcc, exec, s[16:17]
	s_mov_b64 s[0:1], -1
	v_cvt_pk_bf16_f32 v167, v162, v163
	ds_bpermute_b32 v214, v253, v164
	ds_bpermute_b32 v215, v253, v165
	ds_bpermute_b32 v216, v253, v166
	ds_bpermute_b32 v217, v253, v167
	v_lshl_add_u64 v[218:219], v[168:169], 0, v[228:229]
	s_waitcnt lgkmcnt(4)
	global_store_dwordx4 v[226:227], v[222:225], off
	s_cbranch_vccnz .LBB0_328
	v_lshlrev_b64 v[162:163], 6, v[160:161]
	v_lshl_add_u64 v[174:175], s[22:23], 0, v[162:163]
	global_load_dwordx4 v[162:165], v[174:175], off offset:48
	global_load_dwordx4 v[166:169], v[174:175], off offset:32
	global_load_dwordx4 v[170:173], v[174:175], off offset:16
	s_nop 0
	global_load_dwordx4 v[174:177], v[174:175], off
	s_waitcnt vmcnt(0)
	v_add_f32_e32 v166, v166, v167
	v_add_f32_e32 v168, v168, v169
	v_mov_b32_e32 v178, v175
	v_mov_b32_e32 v179, v176
	v_mov_b32_e32 v175, v177
	v_mov_b32_e32 v176, v171
	v_mov_b32_e32 v177, v172
	v_mov_b32_e32 v171, v173
	v_pk_add_f32 v[174:175], v[178:179], v[174:175]
	v_pk_add_f32 v[170:171], v[176:177], v[170:171]
	v_pk_add_f32 v[174:175], v[174:175], v[174:175] op_sel:[0,1] op_sel_hi:[1,0]
	v_pk_add_f32 v[170:171], v[170:171], v[170:171] op_sel:[0,1] op_sel_hi:[1,0]
	v_mov_b32_e32 v175, v162
	v_mov_b32_e32 v171, v163
	v_mov_b32_e32 v167, v164
	v_mov_b32_e32 v169, v165
	v_pk_add_f32 v[162:163], v[174:175], v[170:171]
	v_pk_add_f32 v[164:165], v[166:167], v[168:169]
	s_nop 0
	v_pk_add_f32 v[162:163], v[162:163], v[164:165]
	s_nop 0
	v_add_f32_e32 v161, v162, v163
	v_fmamk_f32 v161, v161, 0x3a800000, v246
	v_cmp_gt_f32_e32 vcc, s83, v161
	v_mul_f32_e32 v162, 0x4f800000, v161
	s_nop 0
	v_cndmask_b32_e32 v161, v161, v162, vcc
	v_sqrt_f32_e32 v162, v161
	s_nop 0
	v_add_u32_e32 v163, -1, v162
	v_fma_f32 v164, -v163, v162, v161
	v_cmp_ge_f32_e64 s[0:1], 0, v164
	v_add_u32_e32 v164, 1, v162
	s_nop 0
	v_cndmask_b32_e64 v163, v162, v163, s[0:1]
	v_fma_f32 v162, -v164, v162, v161
	v_cmp_lt_f32_e64 s[0:1], 0, v162
	s_nop 1
	v_cndmask_b32_e64 v162, v163, v164, s[0:1]
	v_mul_f32_e32 v163, 0x37800000, v162
	v_cndmask_b32_e32 v162, v162, v163, vcc
	v_cmp_class_f32_e32 vcc, v161, v247
	s_nop 1
	v_cndmask_b32_e32 v161, v162, v161, vcc
	v_div_scale_f32 v162, s[0:1], v161, v161, 1.0
	v_rcp_f32_e32 v163, v162
	s_nop 0
	v_fma_f32 v164, -v162, v163, 1.0
	v_fmac_f32_e32 v163, v164, v163
	v_div_scale_f32 v164, vcc, 1.0, v161, 1.0
	v_mul_f32_e32 v165, v164, v163
	v_fma_f32 v166, -v162, v165, v164
	v_fmac_f32_e32 v165, v166, v163
	v_fma_f32 v162, -v162, v165, v164
	v_div_fmas_f32 v162, v162, v163, v165
	v_div_fixup_f32 v178, v162, v161, 1.0
	s_cbranch_execz .LBB0_329

; __device__ __forceinline__ unsigned cvt_pk_bf16(float lo, float hi) { unsigned r; asm volatile("v_cvt_pk_bf16_f32 %0, %1, %2" : "=v"(r) : "v"(lo), "v"(hi)); return r; }
;     __device__ __forceinline__ void operator()(const f32x4 (&acc)[2][2][4][2], const Unit& u, int wr, int wc, int fr, int fq) const {
;     ...
;                     if (ropew) {
;                         f32x4 p0, p1;
; #pragma unroll
;                         for (int e = 0; e < 4; ++e) { p0[e] = __shfl_xor(v0[e], 16); p1[e] = __shfl_xor(v1[e], 16); }
;                         v0 = v0 * c0 + p0 * s0; v1 = v1 * c1 + p1 * s1;
;                     }
;                     v0 = v0 * scr; v1 = v1 * scr;
;                     if (nrmw) { float q = (v0[0] * v0[0] + v0[1] * v0[1]) + (v0[2] * v0[2] + v0[3] * v0[3]) + (v1[0] * v1[0] + v1[1] * v1[1]) + (v1[2] * v1[2] + v1[3] * v1[3]);
;                         q += __shfl_xor(q, 16); q += __shfl_xor(q, 32); mxn[bj] = fmaxf(mxn[bj], q); }
;                     u32x4 w; w.x = cvt_pk_bf16(v0[0], v0[1]); w.y = cvt_pk_bf16(v0[2], v0[3]); w.z = cvt_pk_bf16(v1[0], v1[1]); w.w = cvt_pk_bf16(v1[2], v1[3]);
;                     *(u32x4*)(rowp + bj * HALF) = w;
.LBB0_336:
	v_mov_b64_e32 v[148:149], s[28:29]
	v_mad_i64_i32 v[148:149], s[0:1], v160, s86, v[148:149]
	v_lshl_add_u64 v[148:149], v[184:185], 1, v[148:149]
	s_and_b64 vcc, exec, s[12:13]
	v_cvt_pk_bf16_f32 v156, v156, v157
	v_cvt_pk_bf16_f32 v157, v158, v159
	v_cvt_pk_bf16_f32 v158, v180, v181
	v_cvt_pk_bf16_f32 v159, v150, v151
	ds_bpermute_b32 v222, v253, v156
	ds_bpermute_b32 v223, v253, v157
	ds_bpermute_b32 v224, v253, v158
	ds_bpermute_b32 v225, v253, v159
	v_lshl_add_u64 v[226:227], v[148:149], 0, v[228:229]
	s_waitcnt lgkmcnt(4)
	global_store_dwordx4 v[218:219], v[214:217], off offset:256
	s_cbranch_vccnz .LBB0_338
	ds_bpermute_b32 v150, v235, v140
	ds_bpermute_b32 v151, v235, v141
	ds_bpermute_b32 v156, v235, v136
	ds_bpermute_b32 v158, v235, v142
	ds_bpermute_b32 v159, v235, v143
	ds_bpermute_b32 v157, v235, v137
	ds_bpermute_b32 v160, v235, v138
	ds_bpermute_b32 v161, v235, v139
	s_waitcnt lgkmcnt(0)
	v_pk_mul_f32 v[150:151], v[170:171], v[150:151]
	v_pk_mul_f32 v[158:159], v[172:173], v[158:159]
	v_pk_fma_f32 v[140:141], v[140:141], v[176:177], v[150:151]
	v_pk_mul_f32 v[150:151], v[166:167], v[156:157]
	v_pk_mul_f32 v[156:157], v[164:165], v[160:161]
	v_pk_fma_f32 v[142:143], v[142:143], v[174:175], v[158:159]
	v_pk_fma_f32 v[138:139], v[138:139], v[162:163], v[156:157]
	v_pk_fma_f32 v[136:137], v[136:137], v[168:169], v[150:151]

; __device__ __forceinline__ unsigned cvt_pk_bf16(float lo, float hi) { unsigned r; asm volatile("v_cvt_pk_bf16_f32 %0, %1, %2" : "=v"(r) : "v"(lo), "v"(hi)); return r; }
; __device__ __forceinline__ float row_rstd(const float* part, int row, float eps) {
;     const f32x4* p = (const f32x4*)(part + (size_t)row * 16);
;     const f32x4 a = p[0], b = p[1], c = p[2], d = p[3];
;     const float s = ((a[0] + a[1]) + (a[2] + a[3])) + ((b[0] + b[1]) + (b[2] + b[3])) + ((c[0] + c[1]) + (c[2] + c[3])) + ((d[0] + d[1]) + (d[2] + d[3]));
;     return 1.0f / sqrtf(s * (1.0f / 1024.0f) + eps);
; }
;     __device__ __forceinline__ void operator()(const f32x4 (&acc)[2][2][4][2], const Unit& u, int wr, int wc, int fr, int fq) const {
;     ...
;                     u32x4 w; w.x = cvt_pk_bf16(v0[0], v0[1]); w.y = cvt_pk_bf16(v0[2], v0[3]); w.z = cvt_pk_bf16(v1[0], v1[1]); w.w = cvt_pk_bf16(v1[2], v1[3]);
;                     *(u32x4*)(rowp + bj * HALF) = w;
.LBB0_342:
	v_cvt_pk_bf16_f32 v140, v140, v141
	v_cvt_pk_bf16_f32 v141, v142, v143
	v_cvt_pk_bf16_f32 v142, v136, v137
	v_or_b32_e32 v136, 48, v208
	v_ashrrev_i32_e32 v137, 31, v136
	s_and_b64 vcc, exec, s[16:17]
	s_mov_b64 s[0:1], -1
	v_cvt_pk_bf16_f32 v143, v138, v139
	ds_bpermute_b32 v214, v253, v140
	ds_bpermute_b32 v215, v253, v141
	ds_bpermute_b32 v216, v253, v142
	ds_bpermute_b32 v217, v253, v143
	v_lshl_add_u64 v[218:219], v[148:149], 0, v[228:229]
	s_waitcnt lgkmcnt(4)
	global_store_dwordx4 v[226:227], v[222:225], off
	s_cbranch_vccnz .LBB0_348
	v_lshlrev_b64 v[138:139], 6, v[136:137]
	v_lshl_add_u64 v[142:143], s[22:23], 0, v[138:139]
	global_load_dwordx4 v[138:141], v[142:143], off offset:48
	global_load_dwordx4 v[148:151], v[142:143], off offset:32
	global_load_dwordx4 v[156:159], v[142:143], off offset:16
	global_load_dwordx4 v[160:163], v[142:143], off
	s_waitcnt vmcnt(0)
	v_add_f32_e32 v148, v148, v149
	v_add_f32_e32 v150, v150, v151
	v_mov_b32_e32 v142, v161
	v_mov_b32_e32 v143, v162
	v_mov_b32_e32 v161, v163
	v_pk_add_f32 v[142:143], v[142:143], v[160:161]
	v_mov_b32_e32 v160, v157
	v_mov_b32_e32 v161, v158
	v_mov_b32_e32 v157, v159
	v_pk_add_f32 v[156:157], v[160:161], v[156:157]
	v_pk_add_f32 v[142:143], v[142:143], v[142:143] op_sel:[0,1] op_sel_hi:[1,0]
	v_pk_add_f32 v[156:157], v[156:157], v[156:157] op_sel:[0,1] op_sel_hi:[1,0]
	v_mov_b32_e32 v143, v138
	v_mov_b32_e32 v157, v139
	v_mov_b32_e32 v149, v140
	v_mov_b32_e32 v151, v141
	v_pk_add_f32 v[138:139], v[142:143], v[156:157]
	v_pk_add_f32 v[140:141], v[148:149], v[150:151]
	s_nop 0
	v_pk_add_f32 v[138:139], v[138:139], v[140:141]
	s_nop 0
	v_add_f32_e32 v137, v138, v139
	v_fmamk_f32 v137, v137, 0x3a800000, v246
	v_cmp_gt_f32_e32 vcc, s83, v137
	v_mul_f32_e32 v138, 0x4f800000, v137
	s_nop 0
	v_cndmask_b32_e32 v137, v137, v138, vcc
	v_sqrt_f32_e32 v138, v137
	s_nop 0
	v_add_u32_e32 v139, -1, v138
	v_fma_f32 v140, -v139, v138, v137
	v_cmp_ge_f32_e64 s[0:1], 0, v140
	v_add_u32_e32 v140, 1, v138
	s_nop 0
	v_cndmask_b32_e64 v139, v138, v139, s[0:1]
	v_fma_f32 v138, -v140, v138, v137
	v_cmp_lt_f32_e64 s[0:1], 0, v138
	s_nop 1
	v_cndmask_b32_e64 v138, v139, v140, s[0:1]
	v_mul_f32_e32 v139, 0x37800000, v138
	v_cndmask_b32_e32 v138, v138, v139, vcc
	v_cmp_class_f32_e32 vcc, v137, v247
	s_nop 1
	v_cndmask_b32_e32 v137, v138, v137, vcc
	v_div_scale_f32 v138, s[0:1], v137, v137, 1.0
	v_rcp_f32_e32 v139, v138
	s_nop 0
	v_fma_f32 v140, -v138, v139, 1.0
	v_fmac_f32_e32 v139, v140, v139
	v_div_scale_f32 v140, vcc, 1.0, v137, 1.0
	v_mul_f32_e32 v141, v140, v139
	v_fma_f32 v142, -v138, v141, v140
	v_fmac_f32_e32 v141, v142, v139
	v_fma_f32 v138, -v138, v141, v140
	v_div_fmas_f32 v138, v138, v139, v141
	v_div_fixup_f32 v162, v138, v137, 1.0
	s_cbranch_execz .LBB0_349

; __device__ __forceinline__ unsigned cvt_pk_bf16(float lo, float hi) { unsigned r; asm volatile("v_cvt_pk_bf16_f32 %0, %1, %2" : "=v"(r) : "v"(lo), "v"(hi)); return r; }
;     __device__ __forceinline__ void operator()(const f32x4 (&acc)[2][2][4][2], const Unit& u, int wr, int wc, int fr, int fq) const {
;     ...
;                     if (ropew) {
;                         f32x4 p0, p1;
; #pragma unroll
;                         for (int e = 0; e < 4; ++e) { p0[e] = __shfl_xor(v0[e], 16); p1[e] = __shfl_xor(v1[e], 16); }
;                         v0 = v0 * c0 + p0 * s0; v1 = v1 * c1 + p1 * s1;
;                     }
;                     v0 = v0 * scr; v1 = v1 * scr;
;                     if (nrmw) { float q = (v0[0] * v0[0] + v0[1] * v0[1]) + (v0[2] * v0[2] + v0[3] * v0[3]) + (v1[0] * v1[0] + v1[1] * v1[1]) + (v1[2] * v1[2] + v1[3] * v1[3]);
;                         q += __shfl_xor(q, 16); q += __shfl_xor(q, 32); mxn[bj] = fmaxf(mxn[bj], q); }
;                     u32x4 w; w.x = cvt_pk_bf16(v0[0], v0[1]); w.y = cvt_pk_bf16(v0[2], v0[3]); w.z = cvt_pk_bf16(v1[0], v1[1]); w.w = cvt_pk_bf16(v1[2], v1[3]);
;                     *(u32x4*)(rowp + bj * HALF) = w;
.LBB0_356:
	v_mov_b64_e32 v[112:113], s[28:29]
	v_mad_i64_i32 v[112:113], s[0:1], v136, s86, v[112:113]
	v_lshl_add_u64 v[112:113], v[184:185], 1, v[112:113]
	s_and_b64 vcc, exec, s[12:13]
	v_cvt_pk_bf16_f32 v116, v116, v117
	v_cvt_pk_bf16_f32 v117, v118, v119
	v_cvt_pk_bf16_f32 v118, v164, v165
	v_cvt_pk_bf16_f32 v119, v114, v115
	ds_bpermute_b32 v222, v253, v116
	ds_bpermute_b32 v223, v253, v117
	ds_bpermute_b32 v224, v253, v118
	ds_bpermute_b32 v225, v253, v119
	v_lshl_add_u64 v[226:227], v[112:113], 0, v[228:229]
	s_waitcnt lgkmcnt(4)
	global_store_dwordx4 v[218:219], v[214:217], off offset:256
	s_cbranch_vccnz .LBB0_358
	ds_bpermute_b32 v114, v235, v108
	ds_bpermute_b32 v115, v235, v109
	ds_bpermute_b32 v116, v235, v104
	ds_bpermute_b32 v118, v235, v110
	ds_bpermute_b32 v119, v235, v111
	ds_bpermute_b32 v117, v235, v105
	ds_bpermute_b32 v136, v235, v106
	ds_bpermute_b32 v137, v235, v107
	s_waitcnt lgkmcnt(0)
	v_pk_mul_f32 v[114:115], v[150:151], v[114:115]
	v_pk_mul_f32 v[118:119], v[156:157], v[118:119]
	v_pk_fma_f32 v[108:109], v[108:109], v[160:161], v[114:115]
	v_pk_mul_f32 v[114:115], v[142:143], v[116:117]
	v_pk_mul_f32 v[116:117], v[140:141], v[136:137]
	v_pk_fma_f32 v[110:111], v[110:111], v[158:159], v[118:119]
	v_pk_fma_f32 v[106:107], v[106:107], v[138:139], v[116:117]
	v_pk_fma_f32 v[104:105], v[104:105], v[148:149], v[114:115]

; __device__ __forceinline__ unsigned cvt_pk_bf16(float lo, float hi) { unsigned r; asm volatile("v_cvt_pk_bf16_f32 %0, %1, %2" : "=v"(r) : "v"(lo), "v"(hi)); return r; }
;     __device__ __forceinline__ void operator()(const f32x4 (&acc)[2][2][4][2], const Unit& u, int wr, int wc, int fr, int fq) const {
;     ...
;             if (ropew) {
; #pragma unroll
;                 for (int m = 0; m < 4; ++m) { const f32x4* rp = (const f32x4*)(rope + (size_t)((row0 + ai * HALF + m * 16) & 4095) * 16); rc[m][0] = rp[0]; rc[m][1] = rp[1]; rc[m][2] = rp[2]; rc[m][3] = rp[3]; }
;     ...
;                     u32x4 w; w.x = cvt_pk_bf16(v0[0], v0[1]); w.y = cvt_pk_bf16(v0[2], v0[3]); w.z = cvt_pk_bf16(v1[0], v1[1]); w.w = cvt_pk_bf16(v1[2], v1[3]);
;                     *(u32x4*)(rowp + bj * HALF) = w;
.LBB0_362:
	s_and_b64 vcc, exec, s[12:13]
	v_cvt_pk_bf16_f32 v108, v108, v109
	v_cvt_pk_bf16_f32 v109, v110, v111
	v_cvt_pk_bf16_f32 v110, v104, v105
	v_cvt_pk_bf16_f32 v111, v106, v107
	ds_bpermute_b32 v214, v253, v108
	ds_bpermute_b32 v215, v253, v109
	ds_bpermute_b32 v216, v253, v110
	ds_bpermute_b32 v217, v253, v111
	v_lshl_add_u64 v[218:219], v[112:113], 0, v[228:229]
	s_waitcnt lgkmcnt(4)
	global_store_dwordx4 v[226:227], v[222:225], off
	s_cbranch_vccnz .LBB0_364
	v_add_u32_e32 v48, 0x800, v251
	v_and_b32_e32 v48, 0xfcf0, v48
	v_lshlrev_b32_e32 v60, 2, v48
	global_load_dwordx4 v[128:131], v60, s[72:73] offset:16
	global_load_dwordx4 v[132:135], v60, s[72:73]
	global_load_dwordx4 v[144:147], v60, s[72:73] offset:48
	global_load_dwordx4 v[152:155], v60, s[72:73] offset:32
	global_load_dwordx4 v[96:99], v60, s[72:73] offset:1040
	global_load_dwordx4 v[100:103], v60, s[72:73] offset:1024
	global_load_dwordx4 v[120:123], v60, s[72:73] offset:1072
	global_load_dwordx4 v[124:127], v60, s[72:73] offset:1056
	global_load_dwordx4 v[76:79], v60, s[72:73] offset:2064
	global_load_dwordx4 v[84:87], v60, s[72:73] offset:2048
	global_load_dwordx4 v[88:91], v60, s[72:73] offset:2096
	global_load_dwordx4 v[92:95], v60, s[72:73] offset:2080
	global_load_dwordx4 v[48:51], v60, s[72:73] offset:3088
	global_load_dwordx4 v[52:55], v60, s[72:73] offset:3072
	global_load_dwordx4 v[56:59], v60, s[72:73] offset:3120
	s_nop 0
	global_load_dwordx4 v[60:63], v60, s[72:73] offset:3104

; __device__ __forceinline__ unsigned cvt_pk_bf16(float lo, float hi) { unsigned r; asm volatile("v_cvt_pk_bf16_f32 %0, %1, %2" : "=v"(r) : "v"(lo), "v"(hi)); return r; }
;     __device__ __forceinline__ void operator()(const f32x4 (&acc)[2][2][4][2], const Unit& u, int wr, int wc, int fr, int fq) const {
;     ...
;                     if (ropew) {
;                         f32x4 p0, p1;
; #pragma unroll
;                         for (int e = 0; e < 4; ++e) { p0[e] = __shfl_xor(v0[e], 16); p1[e] = __shfl_xor(v1[e], 16); }
;                         v0 = v0 * c0 + p0 * s0; v1 = v1 * c1 + p1 * s1;
;                     }
;                     v0 = v0 * scr; v1 = v1 * scr;
;                     if (nrmw) { float q = (v0[0] * v0[0] + v0[1] * v0[1]) + (v0[2] * v0[2] + v0[3] * v0[3]) + (v1[0] * v1[0] + v1[1] * v1[1]) + (v1[2] * v1[2] + v1[3] * v1[3]);
;                         q += __shfl_xor(q, 16); q += __shfl_xor(q, 32); mxn[bj] = fmaxf(mxn[bj], q); }
;                     u32x4 w; w.x = cvt_pk_bf16(v0[0], v0[1]); w.y = cvt_pk_bf16(v0[2], v0[3]); w.z = cvt_pk_bf16(v1[0], v1[1]); w.w = cvt_pk_bf16(v1[2], v1[3]);
;                     *(u32x4*)(rowp + bj * HALF) = w;
.LBB0_378:
	v_mov_b64_e32 v[72:73], s[28:29]
	v_mad_i64_i32 v[72:73], s[0:1], v104, s86, v[72:73]
	v_lshl_add_u64 v[72:73], v[184:185], 1, v[72:73]
	s_and_b64 vcc, exec, s[12:13]
	v_cvt_pk_bf16_f32 v80, v80, v81
	v_cvt_pk_bf16_f32 v81, v82, v83
	v_cvt_pk_bf16_f32 v82, v116, v117
	v_cvt_pk_bf16_f32 v83, v74, v75
	ds_bpermute_b32 v222, v253, v80
	ds_bpermute_b32 v223, v253, v81
	ds_bpermute_b32 v224, v253, v82
	ds_bpermute_b32 v225, v253, v83
	v_lshl_add_u64 v[226:227], v[72:73], 0, v[228:229]
	s_waitcnt lgkmcnt(4)
	global_store_dwordx4 v[218:219], v[214:217], off offset:256
	s_cbranch_vccnz .LBB0_380
	ds_bpermute_b32 v74, v235, v68
	ds_bpermute_b32 v75, v235, v69
	ds_bpermute_b32 v80, v235, v64
	ds_bpermute_b32 v82, v235, v70
	ds_bpermute_b32 v83, v235, v71
	ds_bpermute_b32 v81, v235, v65
	ds_bpermute_b32 v104, v235, v66
	ds_bpermute_b32 v105, v235, v67
	s_waitcnt lgkmcnt(6)
	v_pk_mul_f32 v[74:75], v[110:111], v[74:75]
	s_waitcnt lgkmcnt(3)
	v_pk_mul_f32 v[82:83], v[112:113], v[82:83]
	v_pk_fma_f32 v[68:69], v[68:69], v[132:133], v[74:75]
	s_waitcnt lgkmcnt(2)
	v_pk_mul_f32 v[74:75], v[108:109], v[80:81]
	s_waitcnt lgkmcnt(0)
	v_pk_mul_f32 v[80:81], v[106:107], v[104:105]
	v_pk_fma_f32 v[70:71], v[70:71], v[134:135], v[82:83]
	v_pk_fma_f32 v[66:67], v[66:67], v[130:131], v[80:81]
	v_pk_fma_f32 v[64:65], v[64:65], v[128:129], v[74:75]

; __device__ __forceinline__ unsigned cvt_pk_bf16(float lo, float hi) { unsigned r; asm volatile("v_cvt_pk_bf16_f32 %0, %1, %2" : "=v"(r) : "v"(lo), "v"(hi)); return r; }
; __device__ __forceinline__ float row_rstd(const float* part, int row, float eps) {
;     const f32x4* p = (const f32x4*)(part + (size_t)row * 16);
;     const f32x4 a = p[0], b = p[1], c = p[2], d = p[3];
;     const float s = ((a[0] + a[1]) + (a[2] + a[3])) + ((b[0] + b[1]) + (b[2] + b[3])) + ((c[0] + c[1]) + (c[2] + c[3])) + ((d[0] + d[1]) + (d[2] + d[3]));
;     return 1.0f / sqrtf(s * (1.0f / 1024.0f) + eps);
; }
;     __device__ __forceinline__ void operator()(const f32x4 (&acc)[2][2][4][2], const Unit& u, int wr, int wc, int fr, int fq) const {
;     ...
;                     u32x4 w; w.x = cvt_pk_bf16(v0[0], v0[1]); w.y = cvt_pk_bf16(v0[2], v0[3]); w.z = cvt_pk_bf16(v1[0], v1[1]); w.w = cvt_pk_bf16(v1[2], v1[3]);
;                     *(u32x4*)(rowp + bj * HALF) = w;
.LBB0_384:
	v_cvt_pk_bf16_f32 v68, v68, v69
	v_cvt_pk_bf16_f32 v69, v70, v71
	v_cvt_pk_bf16_f32 v70, v64, v65
	v_add_u32_e32 v64, 0x90, v208
	v_ashrrev_i32_e32 v65, 31, v64
	s_and_b64 vcc, exec, s[16:17]
	s_mov_b64 s[0:1], -1
	v_cvt_pk_bf16_f32 v71, v66, v67
	ds_bpermute_b32 v214, v253, v68
	ds_bpermute_b32 v215, v253, v69
	ds_bpermute_b32 v216, v253, v70
	ds_bpermute_b32 v217, v253, v71
	v_lshl_add_u64 v[218:219], v[72:73], 0, v[228:229]
	s_waitcnt lgkmcnt(4)
	global_store_dwordx4 v[226:227], v[222:225], off
	s_cbranch_vccnz .LBB0_390
	v_lshlrev_b64 v[66:67], 6, v[64:65]
	v_lshl_add_u64 v[74:75], s[22:23], 0, v[66:67]
	global_load_dwordx4 v[66:69], v[74:75], off offset:48
	global_load_dwordx4 v[70:73], v[74:75], off offset:32
	global_load_dwordx4 v[80:83], v[74:75], off offset:16
	global_load_dwordx4 v[104:107], v[74:75], off
	s_waitcnt vmcnt(2)
	v_add_f32_e32 v70, v70, v71
	v_add_f32_e32 v72, v72, v73
	s_waitcnt vmcnt(0)
	v_mov_b32_e32 v74, v105
	v_mov_b32_e32 v75, v106
	v_mov_b32_e32 v105, v107
	v_pk_add_f32 v[74:75], v[74:75], v[104:105]
	v_mov_b32_e32 v104, v81
	v_mov_b32_e32 v105, v82
	v_mov_b32_e32 v81, v83
	v_pk_add_f32 v[80:81], v[104:105], v[80:81]
	v_pk_add_f32 v[74:75], v[74:75], v[74:75] op_sel:[0,1] op_sel_hi:[1,0]
	v_pk_add_f32 v[80:81], v[80:81], v[80:81] op_sel:[0,1] op_sel_hi:[1,0]
	v_mov_b32_e32 v75, v66
	v_mov_b32_e32 v81, v67
	v_mov_b32_e32 v71, v68
	v_mov_b32_e32 v73, v69
	v_pk_add_f32 v[66:67], v[74:75], v[80:81]
	v_pk_add_f32 v[68:69], v[70:71], v[72:73]
	s_nop 0
	v_pk_add_f32 v[66:67], v[66:67], v[68:69]
	s_nop 0
	v_add_f32_e32 v65, v66, v67
	v_fmamk_f32 v65, v65, 0x3a800000, v246
	v_cmp_gt_f32_e32 vcc, s83, v65
	v_mul_f32_e32 v66, 0x4f800000, v65
	s_nop 0
	v_cndmask_b32_e32 v65, v65, v66, vcc
	v_sqrt_f32_e32 v66, v65
	s_nop 0
	v_add_u32_e32 v67, -1, v66
	v_fma_f32 v68, -v67, v66, v65
	v_cmp_ge_f32_e64 s[0:1], 0, v68
	v_add_u32_e32 v68, 1, v66
	s_nop 0
	v_cndmask_b32_e64 v67, v66, v67, s[0:1]
	v_fma_f32 v66, -v68, v66, v65
	v_cmp_lt_f32_e64 s[0:1], 0, v66
	s_nop 1
	v_cndmask_b32_e64 v66, v67, v68, s[0:1]
	v_mul_f32_e32 v67, 0x37800000, v66
	v_cndmask_b32_e32 v66, v66, v67, vcc
	v_cmp_class_f32_e32 vcc, v65, v247
	s_nop 1
	v_cndmask_b32_e32 v65, v66, v65, vcc
	v_div_scale_f32 v66, s[0:1], v65, v65, 1.0
	v_rcp_f32_e32 v67, v66
	s_nop 0
	v_fma_f32 v68, -v66, v67, 1.0
	v_fmac_f32_e32 v67, v68, v67
	v_div_scale_f32 v68, vcc, 1.0, v65, 1.0
	v_mul_f32_e32 v69, v68, v67
	v_fma_f32 v70, -v66, v69, v68
	v_fmac_f32_e32 v69, v70, v67
	v_fma_f32 v66, -v66, v69, v68
	v_div_fmas_f32 v66, v66, v67, v69
	v_div_fixup_f32 v74, v66, v65, 1.0
	s_cbranch_execz .LBB0_391

; __device__ __forceinline__ unsigned cvt_pk_bf16(float lo, float hi) { unsigned r; asm volatile("v_cvt_pk_bf16_f32 %0, %1, %2" : "=v"(r) : "v"(lo), "v"(hi)); return r; }
;     __device__ __forceinline__ void operator()(const f32x4 (&acc)[2][2][4][2], const Unit& u, int wr, int wc, int fr, int fq) const {
;     ...
;                     if (ropew) {
;                         f32x4 p0, p1;
; #pragma unroll
;                         for (int e = 0; e < 4; ++e) { p0[e] = __shfl_xor(v0[e], 16); p1[e] = __shfl_xor(v1[e], 16); }
;                         v0 = v0 * c0 + p0 * s0; v1 = v1 * c1 + p1 * s1;
;                     }
;                     v0 = v0 * scr; v1 = v1 * scr;
;                     if (nrmw) { float q = (v0[0] * v0[0] + v0[1] * v0[1]) + (v0[2] * v0[2] + v0[3] * v0[3]) + (v1[0] * v1[0] + v1[1] * v1[1]) + (v1[2] * v1[2] + v1[3] * v1[3]);
;                         q += __shfl_xor(q, 16); q += __shfl_xor(q, 32); mxn[bj] = fmaxf(mxn[bj], q); }
;                     u32x4 w; w.x = cvt_pk_bf16(v0[0], v0[1]); w.y = cvt_pk_bf16(v0[2], v0[3]); w.z = cvt_pk_bf16(v1[0], v1[1]); w.w = cvt_pk_bf16(v1[2], v1[3]);
;                     *(u32x4*)(rowp + bj * HALF) = w;
.LBB0_398:
	v_mov_b64_e32 v[40:41], s[28:29]
	v_mad_i64_i32 v[40:41], s[0:1], v64, s86, v[40:41]
	v_lshl_add_u64 v[40:41], v[184:185], 1, v[40:41]
	s_and_b64 vcc, exec, s[12:13]
	v_cvt_pk_bf16_f32 v44, v44, v45
	v_cvt_pk_bf16_f32 v45, v46, v47
	v_cvt_pk_bf16_f32 v46, v80, v81
	v_cvt_pk_bf16_f32 v47, v42, v43
	ds_bpermute_b32 v222, v253, v44
	ds_bpermute_b32 v223, v253, v45
	ds_bpermute_b32 v224, v253, v46
	ds_bpermute_b32 v225, v253, v47
	v_lshl_add_u64 v[226:227], v[40:41], 0, v[228:229]
	s_waitcnt lgkmcnt(4)
	global_store_dwordx4 v[218:219], v[214:217], off offset:256
	s_cbranch_vccnz .LBB0_400
	ds_bpermute_b32 v42, v235, v36
	ds_bpermute_b32 v43, v235, v37
	ds_bpermute_b32 v44, v235, v32
	ds_bpermute_b32 v46, v235, v38
	ds_bpermute_b32 v47, v235, v39
	ds_bpermute_b32 v45, v235, v33
	ds_bpermute_b32 v64, v235, v34
	ds_bpermute_b32 v65, v235, v35
	s_waitcnt lgkmcnt(6)
	v_pk_mul_f32 v[42:43], v[70:71], v[42:43]
	s_waitcnt lgkmcnt(3)
	v_pk_mul_f32 v[46:47], v[72:73], v[46:47]
	v_pk_fma_f32 v[36:37], v[36:37], v[100:101], v[42:43]
	s_waitcnt lgkmcnt(2)
	v_pk_mul_f32 v[42:43], v[68:69], v[44:45]
	s_waitcnt lgkmcnt(0)
	v_pk_mul_f32 v[44:45], v[66:67], v[64:65]
	v_pk_fma_f32 v[38:39], v[38:39], v[102:103], v[46:47]
	v_pk_fma_f32 v[34:35], v[34:35], v[98:99], v[44:45]
	v_pk_fma_f32 v[32:33], v[32:33], v[96:97], v[42:43]

; __device__ __forceinline__ unsigned cvt_pk_bf16(float lo, float hi) { unsigned r; asm volatile("v_cvt_pk_bf16_f32 %0, %1, %2" : "=v"(r) : "v"(lo), "v"(hi)); return r; }
; __device__ __forceinline__ float row_rstd(const float* part, int row, float eps) {
;     const f32x4* p = (const f32x4*)(part + (size_t)row * 16);
;     const f32x4 a = p[0], b = p[1], c = p[2], d = p[3];
;     const float s = ((a[0] + a[1]) + (a[2] + a[3])) + ((b[0] + b[1]) + (b[2] + b[3])) + ((c[0] + c[1]) + (c[2] + c[3])) + ((d[0] + d[1]) + (d[2] + d[3]));
;     return 1.0f / sqrtf(s * (1.0f / 1024.0f) + eps);
; }
;     __device__ __forceinline__ void operator()(const f32x4 (&acc)[2][2][4][2], const Unit& u, int wr, int wc, int fr, int fq) const {
;     ...
;                     u32x4 w; w.x = cvt_pk_bf16(v0[0], v0[1]); w.y = cvt_pk_bf16(v0[2], v0[3]); w.z = cvt_pk_bf16(v1[0], v1[1]); w.w = cvt_pk_bf16(v1[2], v1[3]);
;                     *(u32x4*)(rowp + bj * HALF) = w;
.LBB0_404:
	v_cvt_pk_bf16_f32 v36, v36, v37
	v_cvt_pk_bf16_f32 v37, v38, v39
	v_cvt_pk_bf16_f32 v38, v32, v33
	v_add_u32_e32 v32, 0xa0, v208
	v_ashrrev_i32_e32 v33, 31, v32
	s_and_b64 vcc, exec, s[16:17]
	s_mov_b64 s[0:1], -1
	v_cvt_pk_bf16_f32 v39, v34, v35
	ds_bpermute_b32 v214, v253, v36
	ds_bpermute_b32 v215, v253, v37
	ds_bpermute_b32 v216, v253, v38
	ds_bpermute_b32 v217, v253, v39
	v_lshl_add_u64 v[218:219], v[40:41], 0, v[228:229]
	s_waitcnt lgkmcnt(4)
	global_store_dwordx4 v[226:227], v[222:225], off
	s_cbranch_vccnz .LBB0_410
	v_lshlrev_b64 v[34:35], 6, v[32:33]
	v_lshl_add_u64 v[46:47], s[22:23], 0, v[34:35]
	global_load_dwordx4 v[34:37], v[46:47], off offset:48
	global_load_dwordx4 v[38:41], v[46:47], off offset:32
	global_load_dwordx4 v[42:45], v[46:47], off offset:16
	global_load_dwordx4 v[64:67], v[46:47], off
	s_waitcnt vmcnt(2)
	v_add_f32_e32 v38, v38, v39
	v_add_f32_e32 v40, v40, v41
	s_waitcnt vmcnt(0)
	v_mov_b32_e32 v46, v65
	v_mov_b32_e32 v47, v66
	v_mov_b32_e32 v65, v67
	v_pk_add_f32 v[46:47], v[46:47], v[64:65]
	v_mov_b32_e32 v64, v43
	v_mov_b32_e32 v65, v44
	v_mov_b32_e32 v43, v45
	v_pk_add_f32 v[42:43], v[64:65], v[42:43]
	v_pk_add_f32 v[46:47], v[46:47], v[46:47] op_sel:[0,1] op_sel_hi:[1,0]
	v_pk_add_f32 v[42:43], v[42:43], v[42:43] op_sel:[0,1] op_sel_hi:[1,0]
	v_mov_b32_e32 v47, v34
	v_mov_b32_e32 v43, v35
	v_mov_b32_e32 v39, v36
	v_mov_b32_e32 v41, v37
	v_pk_add_f32 v[34:35], v[46:47], v[42:43]
	v_pk_add_f32 v[36:37], v[38:39], v[40:41]
	s_nop 0
	v_pk_add_f32 v[34:35], v[34:35], v[36:37]
	s_nop 0
	v_add_f32_e32 v33, v34, v35
	v_fmamk_f32 v33, v33, 0x3a800000, v246
	v_cmp_gt_f32_e32 vcc, s83, v33
	v_mul_f32_e32 v34, 0x4f800000, v33
	s_nop 0
	v_cndmask_b32_e32 v33, v33, v34, vcc
	v_sqrt_f32_e32 v34, v33
	s_nop 0
	v_add_u32_e32 v35, -1, v34
	v_fma_f32 v36, -v35, v34, v33
	v_cmp_ge_f32_e64 s[0:1], 0, v36
	v_add_u32_e32 v36, 1, v34
	s_nop 0
	v_cndmask_b32_e64 v35, v34, v35, s[0:1]
	v_fma_f32 v34, -v36, v34, v33
	v_cmp_lt_f32_e64 s[0:1], 0, v34
	s_nop 1
	v_cndmask_b32_e64 v34, v35, v36, s[0:1]
	v_mul_f32_e32 v35, 0x37800000, v34
	v_cndmask_b32_e32 v34, v34, v35, vcc
	v_cmp_class_f32_e32 vcc, v33, v247
	s_nop 1
	v_cndmask_b32_e32 v33, v34, v33, vcc
	v_div_scale_f32 v34, s[0:1], v33, v33, 1.0
	v_rcp_f32_e32 v35, v34
	s_nop 0
	v_fma_f32 v36, -v34, v35, 1.0
	v_fmac_f32_e32 v35, v36, v35
	v_div_scale_f32 v36, vcc, 1.0, v33, 1.0
	v_mul_f32_e32 v37, v36, v35
	v_fma_f32 v38, -v34, v37, v36
	v_fmac_f32_e32 v37, v38, v35
	v_fma_f32 v34, -v34, v37, v36
	v_div_fmas_f32 v34, v34, v35, v37
	v_div_fixup_f32 v42, v34, v33, 1.0
	s_cbranch_execz .LBB0_411

; __device__ __forceinline__ unsigned cvt_pk_bf16(float lo, float hi) { unsigned r; asm volatile("v_cvt_pk_bf16_f32 %0, %1, %2" : "=v"(r) : "v"(lo), "v"(hi)); return r; }
;     __device__ __forceinline__ void operator()(const f32x4 (&acc)[2][2][4][2], const Unit& u, int wr, int wc, int fr, int fq) const {
;     ...
;                     if (ropew) {
;                         f32x4 p0, p1;
; #pragma unroll
;                         for (int e = 0; e < 4; ++e) { p0[e] = __shfl_xor(v0[e], 16); p1[e] = __shfl_xor(v1[e], 16); }
;                         v0 = v0 * c0 + p0 * s0; v1 = v1 * c1 + p1 * s1;
;                     }
;                     v0 = v0 * scr; v1 = v1 * scr;
;                     if (nrmw) { float q = (v0[0] * v0[0] + v0[1] * v0[1]) + (v0[2] * v0[2] + v0[3] * v0[3]) + (v1[0] * v1[0] + v1[1] * v1[1]) + (v1[2] * v1[2] + v1[3] * v1[3]);
;                         q += __shfl_xor(q, 16); q += __shfl_xor(q, 32); mxn[bj] = fmaxf(mxn[bj], q); }
;                     u32x4 w; w.x = cvt_pk_bf16(v0[0], v0[1]); w.y = cvt_pk_bf16(v0[2], v0[3]); w.z = cvt_pk_bf16(v1[0], v1[1]); w.w = cvt_pk_bf16(v1[2], v1[3]);
;                     *(u32x4*)(rowp + bj * HALF) = w;
.LBB0_418:
	v_mov_b64_e32 v[24:25], s[28:29]
	v_mad_i64_i32 v[24:25], s[0:1], v32, s86, v[24:25]
	v_lshl_add_u64 v[24:25], v[184:185], 1, v[24:25]
	s_and_b64 vcc, exec, s[12:13]
	v_cvt_pk_bf16_f32 v28, v28, v29
	v_cvt_pk_bf16_f32 v29, v30, v31
	v_cvt_pk_bf16_f32 v30, v44, v45
	v_cvt_pk_bf16_f32 v31, v26, v27
	ds_bpermute_b32 v222, v253, v28
	ds_bpermute_b32 v223, v253, v29
	ds_bpermute_b32 v224, v253, v30
	ds_bpermute_b32 v225, v253, v31
	v_lshl_add_u64 v[226:227], v[24:25], 0, v[228:229]
	s_waitcnt lgkmcnt(4)
	global_store_dwordx4 v[218:219], v[214:217], off offset:256
	s_cbranch_vccnz .LBB0_420
	ds_bpermute_b32 v26, v235, v20
	ds_bpermute_b32 v27, v235, v21
	ds_bpermute_b32 v28, v235, v16
	ds_bpermute_b32 v30, v235, v22
	ds_bpermute_b32 v31, v235, v23
	ds_bpermute_b32 v29, v235, v17
	ds_bpermute_b32 v32, v235, v18
	ds_bpermute_b32 v33, v235, v19
	s_waitcnt lgkmcnt(6)
	v_pk_mul_f32 v[26:27], v[38:39], v[26:27]
	s_waitcnt lgkmcnt(3)
	v_pk_mul_f32 v[30:31], v[40:41], v[30:31]
	v_pk_fma_f32 v[20:21], v[20:21], v[84:85], v[26:27]
	s_waitcnt lgkmcnt(2)
	v_pk_mul_f32 v[26:27], v[36:37], v[28:29]
	s_waitcnt lgkmcnt(0)
	v_pk_mul_f32 v[28:29], v[34:35], v[32:33]
	v_pk_fma_f32 v[22:23], v[22:23], v[86:87], v[30:31]
	v_pk_fma_f32 v[18:19], v[18:19], v[78:79], v[28:29]
	v_pk_fma_f32 v[16:17], v[16:17], v[76:77], v[26:27]

; __device__ __forceinline__ unsigned cvt_pk_bf16(float lo, float hi) { unsigned r; asm volatile("v_cvt_pk_bf16_f32 %0, %1, %2" : "=v"(r) : "v"(lo), "v"(hi)); return r; }
; __device__ __forceinline__ float row_rstd(const float* part, int row, float eps) {
;     const f32x4* p = (const f32x4*)(part + (size_t)row * 16);
;     const f32x4 a = p[0], b = p[1], c = p[2], d = p[3];
;     const float s = ((a[0] + a[1]) + (a[2] + a[3])) + ((b[0] + b[1]) + (b[2] + b[3])) + ((c[0] + c[1]) + (c[2] + c[3])) + ((d[0] + d[1]) + (d[2] + d[3]));
;     return 1.0f / sqrtf(s * (1.0f / 1024.0f) + eps);
; }
;     __device__ __forceinline__ void operator()(const f32x4 (&acc)[2][2][4][2], const Unit& u, int wr, int wc, int fr, int fq) const {
;     ...
;                     u32x4 w; w.x = cvt_pk_bf16(v0[0], v0[1]); w.y = cvt_pk_bf16(v0[2], v0[3]); w.z = cvt_pk_bf16(v1[0], v1[1]); w.w = cvt_pk_bf16(v1[2], v1[3]);
;                     *(u32x4*)(rowp + bj * HALF) = w;
.LBB0_424:
	v_cvt_pk_bf16_f32 v20, v20, v21
	v_cvt_pk_bf16_f32 v21, v22, v23
	v_cvt_pk_bf16_f32 v22, v16, v17
	v_add_u32_e32 v16, 0xb0, v208
	v_ashrrev_i32_e32 v17, 31, v16
	s_and_b64 vcc, exec, s[16:17]
	s_mov_b64 s[0:1], -1
	v_cvt_pk_bf16_f32 v23, v18, v19
	ds_bpermute_b32 v214, v253, v20
	ds_bpermute_b32 v215, v253, v21
	ds_bpermute_b32 v216, v253, v22
	ds_bpermute_b32 v217, v253, v23
	v_lshl_add_u64 v[218:219], v[24:25], 0, v[228:229]
	s_waitcnt lgkmcnt(4)
	global_store_dwordx4 v[226:227], v[222:225], off
	s_cbranch_vccnz .LBB0_430
	v_lshlrev_b64 v[18:19], 6, v[16:17]
	v_lshl_add_u64 v[30:31], s[22:23], 0, v[18:19]
	global_load_dwordx4 v[18:21], v[30:31], off offset:48
	global_load_dwordx4 v[22:25], v[30:31], off offset:32
	global_load_dwordx4 v[26:29], v[30:31], off offset:16
	s_nop 0
	global_load_dwordx4 v[30:33], v[30:31], off
	s_waitcnt vmcnt(2)
	v_add_f32_e32 v22, v22, v23
	v_add_f32_e32 v24, v24, v25
	s_waitcnt vmcnt(0)
	v_mov_b32_e32 v34, v31
	v_mov_b32_e32 v35, v32
	v_mov_b32_e32 v31, v33
	v_mov_b32_e32 v32, v27
	v_mov_b32_e32 v33, v28
	v_mov_b32_e32 v27, v29
	v_pk_add_f32 v[30:31], v[34:35], v[30:31]
	v_pk_add_f32 v[26:27], v[32:33], v[26:27]
	v_pk_add_f32 v[30:31], v[30:31], v[30:31] op_sel:[0,1] op_sel_hi:[1,0]
	v_pk_add_f32 v[26:27], v[26:27], v[26:27] op_sel:[0,1] op_sel_hi:[1,0]
	v_mov_b32_e32 v31, v18
	v_mov_b32_e32 v27, v19
	v_mov_b32_e32 v23, v20
	v_mov_b32_e32 v25, v21
	v_pk_add_f32 v[18:19], v[30:31], v[26:27]
	v_pk_add_f32 v[20:21], v[22:23], v[24:25]
	s_nop 0
	v_pk_add_f32 v[18:19], v[18:19], v[20:21]
	s_nop 0
	v_add_f32_e32 v17, v18, v19
	v_fmamk_f32 v17, v17, 0x3a800000, v246
	v_cmp_gt_f32_e32 vcc, s83, v17
	v_mul_f32_e32 v18, 0x4f800000, v17
	s_nop 0
	v_cndmask_b32_e32 v17, v17, v18, vcc
	v_sqrt_f32_e32 v18, v17
	s_nop 0
	v_add_u32_e32 v19, -1, v18
	v_fma_f32 v20, -v19, v18, v17
	v_cmp_ge_f32_e64 s[0:1], 0, v20
	v_add_u32_e32 v20, 1, v18
	s_nop 0
	v_cndmask_b32_e64 v19, v18, v19, s[0:1]
	v_fma_f32 v18, -v20, v18, v17
	v_cmp_lt_f32_e64 s[0:1], 0, v18
	s_nop 1
	v_cndmask_b32_e64 v18, v19, v20, s[0:1]
	v_mul_f32_e32 v19, 0x37800000, v18
	v_cndmask_b32_e32 v18, v18, v19, vcc
	v_cmp_class_f32_e32 vcc, v17, v247
	s_nop 1
	v_cndmask_b32_e32 v17, v18, v17, vcc
	v_div_scale_f32 v18, s[0:1], v17, v17, 1.0
	v_rcp_f32_e32 v19, v18
	s_nop 0
	v_fma_f32 v20, -v18, v19, 1.0
	v_fmac_f32_e32 v19, v20, v19
	v_div_scale_f32 v20, vcc, 1.0, v17, 1.0
	v_mul_f32_e32 v21, v20, v19
	v_fma_f32 v22, -v18, v21, v20
	v_fmac_f32_e32 v21, v22, v19
	v_fma_f32 v18, -v18, v21, v20
	v_div_fmas_f32 v18, v18, v19, v21
	v_div_fixup_f32 v26, v18, v17, 1.0
	s_cbranch_execz .LBB0_431

; __device__ __forceinline__ unsigned cvt_pk_bf16(float lo, float hi) { unsigned r; asm volatile("v_cvt_pk_bf16_f32 %0, %1, %2" : "=v"(r) : "v"(lo), "v"(hi)); return r; }
;     __device__ __forceinline__ void operator()(const f32x4 (&acc)[2][2][4][2], const Unit& u, int wr, int wc, int fr, int fq) const {
;     ...
;                     if (ropew) {
;                         f32x4 p0, p1;
; #pragma unroll
;                         for (int e = 0; e < 4; ++e) { p0[e] = __shfl_xor(v0[e], 16); p1[e] = __shfl_xor(v1[e], 16); }
;                         v0 = v0 * c0 + p0 * s0; v1 = v1 * c1 + p1 * s1;
;                     }
;                     v0 = v0 * scr; v1 = v1 * scr;
;                     if (nrmw) { float q = (v0[0] * v0[0] + v0[1] * v0[1]) + (v0[2] * v0[2] + v0[3] * v0[3]) + (v1[0] * v1[0] + v1[1] * v1[1]) + (v1[2] * v1[2] + v1[3] * v1[3]);
;                         q += __shfl_xor(q, 16); q += __shfl_xor(q, 32); mxn[bj] = fmaxf(mxn[bj], q); }
;                     u32x4 w; w.x = cvt_pk_bf16(v0[0], v0[1]); w.y = cvt_pk_bf16(v0[2], v0[3]); w.z = cvt_pk_bf16(v1[0], v1[1]); w.w = cvt_pk_bf16(v1[2], v1[3]);
;                     *(u32x4*)(rowp + bj * HALF) = w;
.LBB0_438:
	v_mov_b64_e32 v[8:9], s[28:29]
	v_mad_i64_i32 v[8:9], s[0:1], v16, s86, v[8:9]
	v_lshl_add_u64 v[8:9], v[184:185], 1, v[8:9]
	s_and_b64 vcc, exec, s[12:13]
	v_cvt_pk_bf16_f32 v12, v12, v13
	v_cvt_pk_bf16_f32 v13, v14, v15
	v_cvt_pk_bf16_f32 v14, v28, v29
	v_cvt_pk_bf16_f32 v15, v10, v11
	ds_bpermute_b32 v222, v253, v12
	ds_bpermute_b32 v223, v253, v13
	ds_bpermute_b32 v224, v253, v14
	ds_bpermute_b32 v225, v253, v15
	v_lshl_add_u64 v[226:227], v[8:9], 0, v[228:229]
	s_waitcnt lgkmcnt(4)
	global_store_dwordx4 v[218:219], v[214:217], off offset:256
	s_cbranch_vccnz .LBB0_440
	ds_bpermute_b32 v10, v235, v4
	ds_bpermute_b32 v11, v235, v5
	ds_bpermute_b32 v12, v235, v0
	ds_bpermute_b32 v14, v235, v6
	ds_bpermute_b32 v15, v235, v7
	ds_bpermute_b32 v13, v235, v1
	ds_bpermute_b32 v16, v235, v2
	ds_bpermute_b32 v17, v235, v3
	s_waitcnt lgkmcnt(6)
	v_pk_mul_f32 v[10:11], v[22:23], v[10:11]
	s_waitcnt lgkmcnt(3)
	v_pk_mul_f32 v[14:15], v[24:25], v[14:15]
	v_pk_fma_f32 v[4:5], v[4:5], v[52:53], v[10:11]
	s_waitcnt lgkmcnt(2)
	v_pk_mul_f32 v[10:11], v[20:21], v[12:13]
	s_waitcnt lgkmcnt(0)
	v_pk_mul_f32 v[12:13], v[18:19], v[16:17]
	v_pk_fma_f32 v[6:7], v[6:7], v[54:55], v[14:15]
	v_pk_fma_f32 v[2:3], v[2:3], v[50:51], v[12:13]
	v_pk_fma_f32 v[0:1], v[0:1], v[48:49], v[10:11]

; __device__ __forceinline__ unsigned cvt_pk_bf16(float lo, float hi) { unsigned r; asm volatile("v_cvt_pk_bf16_f32 %0, %1, %2" : "=v"(r) : "v"(lo), "v"(hi)); return r; }
;     __device__ __forceinline__ void operator()(const f32x4 (&acc)[2][2][4][2], const Unit& u, int wr, int wc, int fr, int fq) const {
;     ...
;                     u32x4 w; w.x = cvt_pk_bf16(v0[0], v0[1]); w.y = cvt_pk_bf16(v0[2], v0[3]); w.z = cvt_pk_bf16(v1[0], v1[1]); w.w = cvt_pk_bf16(v1[2], v1[3]);
;                     *(u32x4*)(rowp + bj * HALF) = w;
;                 }
;             }
;         }
;         if (nrmw) {
; #pragma unroll
;             for (int bj = 0; bj < 2; ++bj) { float q = mxn[bj];
;                 q = fmaxf(q, __shfl_xor(q, 1)); q = fmaxf(q, __shfl_xor(q, 2)); q = fmaxf(q, __shfl_xor(q, 4)); q = fmaxf(q, __shfl_xor(q, 8));
;                 const int rel = 256 * (u.pn & 1) + 128 * bj + 32 * wc, b = (u.pm * BM) >> 12;
;                 if (fr == 0 && fq == 0) atomicMax((unsigned*)nrm + (typ < 2 ? 256 : 0) + ((b * 2 + ((typ == 1 || typ == 4) ? 1 : 0)) * 8 + (rel >> 6)) * 2 + ((rel >> 5) & 1), __float_as_uint(q * 1.02f)); }
.LBB0_444:
	s_and_b64 vcc, exec, s[60:61]
	v_cvt_pk_bf16_f32 v4, v4, v5
	v_cvt_pk_bf16_f32 v5, v6, v7
	v_cvt_pk_bf16_f32 v6, v0, v1
	v_cvt_pk_bf16_f32 v7, v2, v3
	ds_bpermute_b32 v214, v253, v4
	ds_bpermute_b32 v215, v253, v5
	ds_bpermute_b32 v216, v253, v6
	ds_bpermute_b32 v217, v253, v7
	v_lshl_add_u64 v[218:219], v[8:9], 0, v[228:229]
	s_waitcnt lgkmcnt(4)
	global_store_dwordx4 v[226:227], v[222:225], off
	s_waitcnt lgkmcnt(0)
	global_store_dwordx4 v[218:219], v[214:217], off offset:256
	s_cbranch_vccz .LBB0_456
	ds_bpermute_b32 v0, v237, v209
	v_max_f32_e32 v1, v209, v209
	s_cmp_eq_u32 s34, 1
	s_cselect_b64 s[0:1], -1, 0
	s_and_b64 s[2:3], s[58:59], exec
	s_waitcnt lgkmcnt(0)
	v_max_f32_e32 v0, v0, v0
	v_max_f32_e32 v0, v1, v0
	ds_bpermute_b32 v1, v238, v0
	s_cselect_b32 s2, 0x100, 0
	s_cmp_eq_u32 s34, 4
	s_cselect_b64 s[12:13], -1, 0
	s_or_b64 s[0:1], s[0:1], s[12:13]
	s_waitcnt lgkmcnt(0)
	v_max_f32_e32 v1, v1, v1
	v_max_f32_e32 v0, v0, v1
	ds_bpermute_b32 v1, v239, v0
	s_and_b64 s[0:1], s[0:1], exec
	s_cselect_b32 s3, 8, 0
	s_waitcnt lgkmcnt(0)
	v_max_f32_e32 v1, v1, v1
	v_max_f32_e32 v0, v0, v1
	ds_bpermute_b32 v1, v240, v0
	s_and_saveexec_b64 s[0:1], s[8:9]
	s_cbranch_execz .LBB0_450
	s_waitcnt lgkmcnt(0)
	v_max_f32_e32 v1, v1, v1
	v_max_f32_e32 v0, v0, v0
	v_max_f32_e32 v0, v0, v1
	s_mov_b64 s[12:13], exec
	v_mul_f32_e32 v0, 0x3f828f5c, v0
	s_mov_b32 s14, 0
